# stack plus SGU LDS-transpose write-back, batched prologue loads, P.V step first eight slots at priority 1
# speedup vs baseline: 1.0112x; 1.0021x over previous
; #define LAS __attribute__((address_space(3)))
; __device__ __forceinline__ unsigned cvtpk_s(float lo, float hi) { return cvt_pk_bf16(lo, hi); }
; template <bool SLOW> ...
;     ...
;     bf16x8 kf[8];
; #pragma unroll
;     for (int d0 = 0; d0 < 4; ++d0) { LAS const unsigned char* kp = ((d0 & 1) ? kb : ka) + (d0 >> 1) * 512; kf[d0] = *(LAS const bf16x8*)(kp); }
; #pragma unroll
;     for (int d0 = 0; d0 < 4; ++d0) { LAS const unsigned char* kp = ((d0 & 1) ? kb : ka) + (d0 >> 1) * 512; kf[4 + d0] = *(LAS const bf16x8*)(kp + 4096); }
;     __builtin_amdgcn_s_setprio(2);
;     p0 = ATT_MFMA(kf[0], qr[0], negm);
; #pragma unroll
;     for (int d0 = 1; d0 < 4; ++d0) p0 = ATT_MFMA(kf[d0], qr[d0], p0);
;     if (!SLOW) __builtin_amdgcn_sched_barrier(0);
;     if (SLOW) {
;         p1 = ATT_MFMA(kf[4], qr[0], negm);
; #pragma unroll
;         for (int d0 = 1; d0 < 4; ++d0) p1 = ATT_MFMA(kf[4 + d0], qr[d0], p1);
;         __builtin_amdgcn_s_setprio(0);
;         __builtin_amdgcn_sched_barrier(0);
;     }
;     if (SLOW) {
;         int dq = qpos - kv0 - 4 * hi; asm volatile("" : "+v"(dq));
; #pragma unroll
;         for (int r = 0; r < 16; ++r) { const int cr = (r & 3) + 8 * (r >> 2); p0[r] = (cr > dq) ? -INFINITY : p0[r]; p1[r] = (cr + 32 > dq) ? -INFINITY : p1[r]; }
;     }
;     if (SLOW && first) {
;         float rm = fmaxf(p0[0], p1[0]);
; #pragma unroll
;         for (int r = 1; r < 16; ++r) rm = fmaxf(rm, fmaxf(p0[r], p1[r]));
;         rm = fmaxf(rm, __shfl_xor(rm, 32));
; #pragma unroll
;         for (int r = 0; r < 16; ++r) { p0[r] -= rm; p1[r] -= rm; negm[r] = -rm; }
;     }
;     float sa = 0.f, sb = 0.f;
;     if (!SLOW) {
; #pragma unroll
;         for (int g = 0; g < 4; ++g) {
;             p1 = (g == 0) ? ATT_MFMA(kf[4], qr[0], negm) : ATT_MFMA(kf[4 + g], qr[g], p1);
; #pragma unroll
;             for (int r = 4 * g; r < 4 * g + 4; r += 2) { p0[r] = __builtin_amdgcn_exp2f(p0[r]); p0[r + 1] = __builtin_amdgcn_exp2f(p0[r + 1]); sa = fadd_s(sa, p0[r]); sb = fadd_s(sb, p0[r + 1]); }
;             if (g & 1) { const int w = g >> 1;
; #pragma unroll
;                 for (int k = 0; k < 4; ++k) pw[w][k] = cvtpk_s(p0[8 * w + 2 * k], p0[8 * w + 2 * k + 1]); }
;             dma_piece(dma, g);
;             __builtin_amdgcn_sched_barrier(0);
;         }
;         l += sa + sb;
;         __builtin_amdgcn_s_setprio(0);
;     } else {
; #pragma unroll
.LBB0_58:
	s_add_i32 s12, s78, 0xffff8000
	s_cmp_lg_u32 s78, 0
	s_cselect_b32 s12, s12, 0x18000
	s_add_i32 s12, s12, 0
	s_add_i32 s13, s12, s59
	s_add_i32 s24, s18, s12
	s_add_i32 s12, s78, 0
	v_add_u32_e32 v96, s12, v143
	v_add_u32_e32 v97, s12, v171
	ds_read_b128 v[80:83], v96
	ds_read_b128 v[84:87], v97
	ds_read_b128 v[88:91], v96 offset:512
	ds_read_b128 v[92:95], v97 offset:512
	ds_read_b128 v[128:131], v96 offset:4096
	ds_read_b128 v[132:135], v97 offset:4096
	ds_read_b128 v[174:177], v96 offset:4608
	ds_read_b128 v[178:181], v97 offset:4608
	v_add_u32_e32 v149, s12, v167
	s_setprio 2
	s_waitcnt lgkmcnt(7)
	v_mfma_f32_32x32x16_bf16 v[96:111], v[80:83], v[112:115], v[64:79]
	s_waitcnt lgkmcnt(6)
	v_mfma_f32_32x32x16_bf16 v[96:111], v[84:87], v[116:119], v[96:111]
	s_waitcnt lgkmcnt(5)
	v_mfma_f32_32x32x16_bf16 v[96:111], v[88:91], v[120:123], v[96:111]
	s_waitcnt lgkmcnt(4)
	v_mfma_f32_32x32x16_bf16 v[96:111], v[92:95], v[124:127], v[96:111]
	s_waitcnt lgkmcnt(3)
	v_mfma_f32_32x32x16_bf16 v[80:95], v[128:131], v[112:115], v[64:79]
	s_nop 9
	v_exp_f32_e32 v96, v96
	v_exp_f32_e32 v97, v97
	v_exp_f32_e32 v98, v98
	v_exp_f32_e32 v99, v99
	v_add_f32_e32 v128, 0, v96
	v_add_f32_e32 v129, 0, v97
	s_mov_b32 s12, m0
	s_mov_b32 m0, s13
	s_nop 0
	global_load_lds_dwordx4 v[150:151], off
	s_mov_b32 m0, s12
	s_nop 0
	v_add_f32_e32 v128, v98, v128
	v_add_f32_e32 v129, v99, v129
	s_waitcnt lgkmcnt(2)
	v_mfma_f32_32x32x16_bf16 v[80:95], v[132:135], v[116:119], v[80:95]
	v_exp_f32_e32 v100, v100
	v_exp_f32_e32 v101, v101
	v_exp_f32_e32 v102, v102
	v_exp_f32_e32 v103, v103
	v_add_f32_e32 v128, v100, v128
	v_add_f32_e32 v129, v101, v129
	v_cvt_pk_bf16_f32 v96, v96, v97
	v_cvt_pk_bf16_f32 v97, v98, v99
	v_cvt_pk_bf16_f32 v98, v100, v101
	v_lshl_add_u64 v[100:101], v[150:151], 0, s[16:17]
	s_add_i32 s12, s13, 0x2000
	s_mov_b32 s13, m0
	s_mov_b32 m0, s12
	s_nop 0
	global_load_lds_dwordx4 v[100:101], off
	s_mov_b32 m0, s13
	v_cvt_pk_bf16_f32 v99, v102, v103
	v_add_f32_e32 v128, v102, v128
	v_add_f32_e32 v129, v103, v129
	s_waitcnt lgkmcnt(1)
	v_mfma_f32_32x32x16_bf16 v[80:95], v[174:177], v[120:123], v[80:95]
	v_exp_f32_e32 v100, v104
	v_exp_f32_e32 v101, v105
	v_exp_f32_e32 v104, v106
	v_exp_f32_e32 v105, v107
	v_add_f32_e32 v102, v100, v128
	v_add_f32_e32 v103, v101, v129
	s_mov_b32 s12, m0
	s_mov_b32 m0, s24
	s_nop 0
	global_load_lds_dwordx4 v[152:153], off
	s_mov_b32 m0, s12
	s_nop 0
	v_add_f32_e32 v102, v104, v102
	v_add_f32_e32 v103, v105, v103
	s_waitcnt lgkmcnt(0)
	v_mfma_f32_32x32x16_bf16 v[80:95], v[178:181], v[124:127], v[80:95]
	v_exp_f32_e32 v106, v108
	v_exp_f32_e32 v107, v109
	v_exp_f32_e32 v108, v110
	v_exp_f32_e32 v109, v111
	v_add_f32_e32 v102, v106, v102
	v_add_f32_e32 v103, v107, v103
	v_cvt_pk_bf16_f32 v100, v100, v101
	v_cvt_pk_bf16_f32 v101, v104, v105
	v_lshl_add_u64 v[104:105], v[152:153], 0, s[0:1]
	s_add_i32 s12, s24, 0x400
	s_mov_b32 s13, m0
	s_mov_b32 m0, s12
	s_nop 0
	global_load_lds_dwordx4 v[104:105], off
	s_mov_b32 m0, s13
	s_nop 0
	v_add_f32_e32 v110, v108, v102
	v_add_f32_e32 v111, v109, v103
	v_cvt_pk_bf16_f32 v102, v106, v107
	v_cvt_pk_bf16_f32 v103, v108, v109
	s_nop 0
	v_add_f32_e32 v104, v110, v111
	v_add_f32_e32 v173, v173, v104
	s_setprio 0
	ds_read_b64_tr_b16 v[104:105], v149 offset:16384
	ds_read_b64_tr_b16 v[106:107], v149 offset:16896
	ds_read_b64_tr_b16 v[108:109], v149 offset:20480
	ds_read_b64_tr_b16 v[110:111], v149 offset:20992
	ds_read_b64_tr_b16 v[132:133], v149 offset:24576
	ds_read_b64_tr_b16 v[134:135], v149 offset:25088
	ds_read_b64_tr_b16 v[128:129], v149 offset:28672
	ds_read_b64_tr_b16 v[130:131], v149 offset:29184
	s_waitcnt vmcnt(8) lgkmcnt(0)
	s_barrier
; #define LAS __attribute__((address_space(3)))
; __device__ __forceinline__ unsigned cvtpk_s(float lo, float hi) { return cvt_pk_bf16(lo, hi); }
; #define ATT_MFMA(a, b, c) __builtin_amdgcn_mfma_f32_32x32x16_bf16(a, b, c, 0, 0, 0)
; __device__ __forceinline__ float fadd_s(float a, float b) { float r = a + b; asm("" : "+v"(r)); return r; }
; #define ATT_VRD(j) do { lo[j] = vtr(vb + ((j) & 3) * 4096 + ((j) >> 2) * 1024); hh[j] = vtr(vb + ((j) & 3) * 4096 + ((j) >> 2) * 1024 + 512); } while (0)
; __device__ __forceinline__ void stepY(f32x16 (&o)[4], u32x4 (&pw)[4], f32x16& p1, float& l, LAS const unsigned char* vb, const s16x4 (&vlo)[4], const s16x4 (&vhh)[4], const DmaT& dma) {
;     __builtin_amdgcn_sched_barrier(0);
;     s16x4 lo[16], hh[16];
;     ...
; #pragma unroll
;     for (int j = 0; j < 4; ++j) { lo[j] = vlo[j]; hh[j] = vhh[j]; }
;     float sa = 0.f, sb = 0.f;
; #pragma unroll
;     for (int j = 0; j < 16; ++j) {
;         if (j + 4 < 16) ATT_VRD(j + 4);
;         { const bf16x8 vf = (bf16x8){lo[j][0], lo[j][1], lo[j][2], lo[j][3], hh[j][0], hh[j][1], hh[j][2], hh[j][3]};
;           o[j & 3] = ATT_MFMA(__builtin_bit_cast(bf16x8, pw[j >> 2]), vf, o[j & 3]); }
;         if (j < 8) { p1[2 * j] = __builtin_amdgcn_exp2f(p1[2 * j]); p1[2 * j + 1] = __builtin_amdgcn_exp2f(p1[2 * j + 1]); sa = fadd_s(sa, p1[2 * j]); sb = fadd_s(sb, p1[2 * j + 1]); }
;         if (j == 3 || j == 7) { const int w = j >> 2;
; #pragma unroll
;             for (int k = 0; k < 4; ++k) pw[2 + w][k] = cvtpk_s(p1[8 * w + 2 * k], p1[8 * w + 2 * k + 1]); }
;         if (j >= 8 && j < 12) dma_piece(dma, j - 8);
;         __builtin_amdgcn_sched_barrier(0);
;     }
;     ...
;     l += sa + sb;
; }
	s_setprio 1
	s_waitcnt lgkmcnt(6)
	v_mfma_f32_32x32x16_bf16 v[0:15], v[96:99], v[104:107], v[0:15]
	v_exp_f32_e32 v80, v80
	ds_read_b64_tr_b16 v[174:175], v149 offset:17408
	ds_read_b64_tr_b16 v[176:177], v149 offset:17920
	v_exp_f32_e32 v81, v81
	v_add_f32_e32 v182, 0, v80
	v_add_f32_e32 v183, 0, v81
	s_waitcnt lgkmcnt(6)
	v_mfma_f32_32x32x16_bf16 v[16:31], v[96:99], v[108:111], v[16:31]
	v_exp_f32_e32 v82, v82
	ds_read_b64_tr_b16 v[178:179], v149 offset:21504
	ds_read_b64_tr_b16 v[180:181], v149 offset:22016
	v_exp_f32_e32 v83, v83
	v_add_f32_e32 v186, v82, v182
	v_add_f32_e32 v187, v83, v183
	s_waitcnt lgkmcnt(6)
	v_mfma_f32_32x32x16_bf16 v[32:47], v[96:99], v[132:135], v[32:47]
	v_exp_f32_e32 v84, v84
	ds_read_b64_tr_b16 v[182:183], v149 offset:25600
	ds_read_b64_tr_b16 v[184:185], v149 offset:26112
	v_exp_f32_e32 v85, v85
	v_add_f32_e32 v190, v84, v186
	v_add_f32_e32 v191, v85, v187
	s_waitcnt lgkmcnt(6)
	v_mfma_f32_32x32x16_bf16 v[48:63], v[96:99], v[128:131], v[48:63]
	v_exp_f32_e32 v86, v86
	ds_read_b64_tr_b16 v[186:187], v149 offset:29696
	ds_read_b64_tr_b16 v[188:189], v149 offset:30208
	v_exp_f32_e32 v87, v87
	v_cvt_pk_bf16_f32 v206, v80, v81
	v_add_f32_e32 v190, v86, v190
	v_add_f32_e32 v191, v87, v191
	v_cvt_pk_bf16_f32 v207, v82, v83
	v_cvt_pk_bf16_f32 v208, v84, v85
	v_cvt_pk_bf16_f32 v209, v86, v87
	s_waitcnt lgkmcnt(6)
	v_mfma_f32_32x32x16_bf16 v[0:15], v[100:103], v[174:177], v[0:15]
	ds_read_b64_tr_b16 v[210:211], v149 offset:18432
	ds_read_b64_tr_b16 v[212:213], v149 offset:18944
	v_exp_f32_e32 v88, v88
	v_exp_f32_e32 v89, v89
	v_add_f32_e32 v190, v88, v190
	v_add_f32_e32 v191, v89, v191
	s_waitcnt lgkmcnt(6)
	v_mfma_f32_32x32x16_bf16 v[16:31], v[100:103], v[178:181], v[16:31]
	ds_read_b64_tr_b16 v[174:175], v149 offset:22528
	ds_read_b64_tr_b16 v[176:177], v149 offset:23040
	v_exp_f32_e32 v90, v90
	v_exp_f32_e32 v91, v91
	v_add_f32_e32 v190, v90, v190
	v_add_f32_e32 v191, v91, v191
	s_waitcnt lgkmcnt(6)
	v_mfma_f32_32x32x16_bf16 v[32:47], v[100:103], v[182:185], v[32:47]
	ds_read_b64_tr_b16 v[178:179], v149 offset:26624
	ds_read_b64_tr_b16 v[180:181], v149 offset:27136
	v_exp_f32_e32 v92, v92
	v_exp_f32_e32 v93, v93
	v_add_f32_e32 v190, v92, v190
	v_add_f32_e32 v191, v93, v191
	s_waitcnt lgkmcnt(6)
	v_mfma_f32_32x32x16_bf16 v[48:63], v[100:103], v[186:189], v[48:63]
	ds_read_b64_tr_b16 v[182:183], v149 offset:30720
	ds_read_b64_tr_b16 v[184:185], v149 offset:31232
	v_exp_f32_e32 v94, v94
	v_exp_f32_e32 v95, v95
	v_cvt_pk_bf16_f32 v186, v88, v89
	v_cvt_pk_bf16_f32 v187, v90, v91
	v_add_f32_e32 v190, v94, v190
	v_add_f32_e32 v191, v95, v191
	v_cvt_pk_bf16_f32 v188, v92, v93
	v_cvt_pk_bf16_f32 v189, v94, v95
	s_setprio 0
	s_waitcnt lgkmcnt(6)
	v_mfma_f32_32x32x16_bf16 v[0:15], v[206:209], v[210:213], v[0:15]
	ds_read_b64_tr_b16 v[214:215], v149 offset:19456
	ds_read_b64_tr_b16 v[216:217], v149 offset:19968
	s_waitcnt lgkmcnt(6)
	v_mfma_f32_32x32x16_bf16 v[16:31], v[206:209], v[174:177], v[16:31]
	ds_read_b64_tr_b16 v[210:211], v149 offset:23552
	ds_read_b64_tr_b16 v[212:213], v149 offset:24064
	s_waitcnt lgkmcnt(6)
	v_mfma_f32_32x32x16_bf16 v[32:47], v[206:209], v[178:181], v[32:47]
	ds_read_b64_tr_b16 v[174:175], v149 offset:27648
	ds_read_b64_tr_b16 v[176:177], v149 offset:28160
	s_waitcnt lgkmcnt(6)
	v_mfma_f32_32x32x16_bf16 v[48:63], v[206:209], v[182:185], v[48:63]
	ds_read_b64_tr_b16 v[178:179], v149 offset:31744
	ds_read_b64_tr_b16 v[180:181], v149 offset:32256
	s_waitcnt lgkmcnt(6)
	v_mfma_f32_32x32x16_bf16 v[0:15], v[186:189], v[214:217], v[0:15]
	s_waitcnt lgkmcnt(4)
	v_mfma_f32_32x32x16_bf16 v[16:31], v[186:189], v[210:213], v[16:31]
	s_waitcnt lgkmcnt(2)
	v_mfma_f32_32x32x16_bf16 v[32:47], v[186:189], v[174:177], v[32:47]
	s_waitcnt lgkmcnt(0)
	v_mfma_f32_32x32x16_bf16 v[48:63], v[186:189], v[178:181], v[48:63]
	s_add_i32 s12, s78, 0x8000
	s_waitcnt lgkmcnt(0)
	s_barrier
	s_cmp_lg_u32 s78, 0x18000
	v_add_f32_e32 v149, v190, v191
	s_cselect_b32 s78, s12, 0
	s_add_i32 s19, s19, -1
	v_lshl_add_u64 v[150:151], v[150:151], 0, s[50:51]
	v_lshl_add_u64 v[152:153], v[152:153], 0, s[50:51]
	s_cmp_eq_u32 s19, 0
	v_add_f32_e32 v173, v173, v149
	s_cbranch_scc0 .LBB0_58
	s_add_i32 s80, s66, -1
	s_cmp_ge_i32 s80, s70
	s_cbranch_scc0 .LBB0_61
	s_branch .LBB0_78

; #define LAS __attribute__((address_space(3)))
; __device__ __forceinline__ unsigned cvtpk_s(float lo, float hi) { return cvt_pk_bf16(lo, hi); }
; template <bool SLOW> ...
;     ...
;     bf16x8 kf[8];
; #pragma unroll
;     for (int d0 = 0; d0 < 4; ++d0) { LAS const unsigned char* kp = ((d0 & 1) ? kb : ka) + (d0 >> 1) * 512; kf[d0] = *(LAS const bf16x8*)(kp); }
; #pragma unroll
;     for (int d0 = 0; d0 < 4; ++d0) { LAS const unsigned char* kp = ((d0 & 1) ? kb : ka) + (d0 >> 1) * 512; kf[4 + d0] = *(LAS const bf16x8*)(kp + 4096); }
;     __builtin_amdgcn_s_setprio(2);
;     p0 = ATT_MFMA(kf[0], qr[0], negm);
; #pragma unroll
;     for (int d0 = 1; d0 < 4; ++d0) p0 = ATT_MFMA(kf[d0], qr[d0], p0);
;     if (!SLOW) __builtin_amdgcn_sched_barrier(0);
;     if (SLOW) {
;         p1 = ATT_MFMA(kf[4], qr[0], negm);
; #pragma unroll
;         for (int d0 = 1; d0 < 4; ++d0) p1 = ATT_MFMA(kf[4 + d0], qr[d0], p1);
;         __builtin_amdgcn_s_setprio(0);
;         __builtin_amdgcn_sched_barrier(0);
;     }
;     if (SLOW) {
;         int dq = qpos - kv0 - 4 * hi; asm volatile("" : "+v"(dq));
; #pragma unroll
;         for (int r = 0; r < 16; ++r) { const int cr = (r & 3) + 8 * (r >> 2); p0[r] = (cr > dq) ? -INFINITY : p0[r]; p1[r] = (cr + 32 > dq) ? -INFINITY : p1[r]; }
;     }
;     if (SLOW && first) {
;         float rm = fmaxf(p0[0], p1[0]);
; #pragma unroll
;         for (int r = 1; r < 16; ++r) rm = fmaxf(rm, fmaxf(p0[r], p1[r]));
;         rm = fmaxf(rm, __shfl_xor(rm, 32));
; #pragma unroll
;         for (int r = 0; r < 16; ++r) { p0[r] -= rm; p1[r] -= rm; negm[r] = -rm; }
;     }
;     float sa = 0.f, sb = 0.f;
;     if (!SLOW) {
; #pragma unroll
;         for (int g = 0; g < 4; ++g) {
;             p1 = (g == 0) ? ATT_MFMA(kf[4], qr[0], negm) : ATT_MFMA(kf[4 + g], qr[g], p1);
; #pragma unroll
;             for (int r = 4 * g; r < 4 * g + 4; r += 2) { p0[r] = __builtin_amdgcn_exp2f(p0[r]); p0[r + 1] = __builtin_amdgcn_exp2f(p0[r + 1]); sa = fadd_s(sa, p0[r]); sb = fadd_s(sb, p0[r + 1]); }
;             if (g & 1) { const int w = g >> 1;
; #pragma unroll
;                 for (int k = 0; k < 4; ++k) pw[w][k] = cvtpk_s(p0[8 * w + 2 * k], p0[8 * w + 2 * k + 1]); }
;             dma_piece(dma, g);
;             __builtin_amdgcn_sched_barrier(0);
;         }
;         l += sa + sb;
;         __builtin_amdgcn_s_setprio(0);
;     } else {
; #pragma unroll
.LBB0_93:
	s_add_i32 s12, s54, 0xffff8000
	s_cmp_lg_u32 s54, 0
	s_cselect_b32 s12, s12, 0x18000
	s_add_i32 s12, s12, 0
	s_add_i32 s25, s12, s59
	s_add_i32 s24, s18, s12
	s_add_i32 s12, s54, 0
	v_add_u32_e32 v96, s12, v143
	v_add_u32_e32 v97, s12, v171
	ds_read_b128 v[80:83], v96
	ds_read_b128 v[84:87], v97
	ds_read_b128 v[88:91], v96 offset:512
	ds_read_b128 v[92:95], v97 offset:512
	ds_read_b128 v[128:131], v96 offset:4096
	ds_read_b128 v[132:135], v97 offset:4096
	ds_read_b128 v[150:153], v96 offset:4608
	ds_read_b128 v[174:177], v97 offset:4608
	v_add_u32_e32 v147, s12, v167
	s_setprio 2
	s_waitcnt lgkmcnt(7)
	v_mfma_f32_32x32x16_bf16 v[96:111], v[80:83], v[112:115], v[64:79]
	s_waitcnt lgkmcnt(6)
	v_mfma_f32_32x32x16_bf16 v[96:111], v[84:87], v[116:119], v[96:111]
	s_waitcnt lgkmcnt(5)
	v_mfma_f32_32x32x16_bf16 v[96:111], v[88:91], v[120:123], v[96:111]
	s_waitcnt lgkmcnt(4)
	v_mfma_f32_32x32x16_bf16 v[96:111], v[92:95], v[124:127], v[96:111]
	s_waitcnt lgkmcnt(3)
	v_mfma_f32_32x32x16_bf16 v[80:95], v[128:131], v[112:115], v[64:79]
	s_nop 9
	v_exp_f32_e32 v96, v96
	v_exp_f32_e32 v97, v97
	v_exp_f32_e32 v98, v98
	v_exp_f32_e32 v99, v99
	v_add_f32_e32 v128, 0, v96
	v_add_f32_e32 v129, 0, v97
	s_nop 0
	v_add_f32_e32 v128, v98, v128
	v_add_f32_e32 v129, v99, v129
	s_waitcnt lgkmcnt(2)
	v_mfma_f32_32x32x16_bf16 v[80:95], v[132:135], v[116:119], v[80:95]
	v_exp_f32_e32 v100, v100
	v_exp_f32_e32 v101, v101
	v_exp_f32_e32 v102, v102
	v_exp_f32_e32 v103, v103
	v_add_f32_e32 v128, v100, v128
	v_add_f32_e32 v129, v101, v129
	v_cvt_pk_bf16_f32 v96, v96, v97
	v_add_f32_e32 v128, v102, v128
	v_add_f32_e32 v129, v103, v129
	v_cvt_pk_bf16_f32 v97, v98, v99
	v_cvt_pk_bf16_f32 v98, v100, v101
	v_cvt_pk_bf16_f32 v99, v102, v103
	s_waitcnt lgkmcnt(1)
	v_mfma_f32_32x32x16_bf16 v[80:95], v[150:153], v[120:123], v[80:95]
	v_exp_f32_e32 v100, v104
	v_exp_f32_e32 v101, v105
	v_exp_f32_e32 v104, v106
	v_exp_f32_e32 v105, v107
	v_add_f32_e32 v102, v100, v128
	v_add_f32_e32 v103, v101, v129
	s_nop 0
	v_add_f32_e32 v102, v104, v102
	v_add_f32_e32 v103, v105, v103
	s_waitcnt lgkmcnt(0)
	v_mfma_f32_32x32x16_bf16 v[80:95], v[174:177], v[124:127], v[80:95]
	v_exp_f32_e32 v106, v108
	v_exp_f32_e32 v107, v109
	v_exp_f32_e32 v108, v110
	v_exp_f32_e32 v109, v111
	v_add_f32_e32 v102, v106, v102
	v_add_f32_e32 v103, v107, v103
	v_cvt_pk_bf16_f32 v100, v100, v101
	v_add_f32_e32 v110, v108, v102
	v_add_f32_e32 v111, v109, v103
	v_cvt_pk_bf16_f32 v101, v104, v105
	v_cvt_pk_bf16_f32 v102, v106, v107
	v_cvt_pk_bf16_f32 v103, v108, v109
	s_nop 0
	v_add_f32_e32 v104, v110, v111
	v_add_f32_e32 v173, v173, v104
	s_setprio 0
	ds_read_b64_tr_b16 v[104:105], v147 offset:16384
	ds_read_b64_tr_b16 v[106:107], v147 offset:16896
	ds_read_b64_tr_b16 v[108:109], v147 offset:20480
	ds_read_b64_tr_b16 v[110:111], v147 offset:20992
	ds_read_b64_tr_b16 v[132:133], v147 offset:24576
	ds_read_b64_tr_b16 v[134:135], v147 offset:25088
	ds_read_b64_tr_b16 v[128:129], v147 offset:28672
	ds_read_b64_tr_b16 v[130:131], v147 offset:29184
	s_waitcnt lgkmcnt(0)
	s_barrier
; #define LAS __attribute__((address_space(3)))
; __device__ __forceinline__ unsigned cvtpk_s(float lo, float hi) { return cvt_pk_bf16(lo, hi); }
; #define ATT_MFMA(a, b, c) __builtin_amdgcn_mfma_f32_32x32x16_bf16(a, b, c, 0, 0, 0)
; __device__ __forceinline__ float fadd_s(float a, float b) { float r = a + b; asm("" : "+v"(r)); return r; }
; #define ATT_VRD(j) do { lo[j] = vtr(vb + ((j) & 3) * 4096 + ((j) >> 2) * 1024); hh[j] = vtr(vb + ((j) & 3) * 4096 + ((j) >> 2) * 1024 + 512); } while (0)
; __device__ __forceinline__ void stepY(f32x16 (&o)[4], u32x4 (&pw)[4], f32x16& p1, float& l, LAS const unsigned char* vb, const s16x4 (&vlo)[4], const s16x4 (&vhh)[4], const DmaT& dma) {
;     __builtin_amdgcn_sched_barrier(0);
;     s16x4 lo[16], hh[16];
;     ...
; #pragma unroll
;     for (int j = 0; j < 4; ++j) { lo[j] = vlo[j]; hh[j] = vhh[j]; }
;     float sa = 0.f, sb = 0.f;
; #pragma unroll
;     for (int j = 0; j < 16; ++j) {
;         if (j + 4 < 16) ATT_VRD(j + 4);
;         { const bf16x8 vf = (bf16x8){lo[j][0], lo[j][1], lo[j][2], lo[j][3], hh[j][0], hh[j][1], hh[j][2], hh[j][3]};
;           o[j & 3] = ATT_MFMA(__builtin_bit_cast(bf16x8, pw[j >> 2]), vf, o[j & 3]); }
;         if (j < 8) { p1[2 * j] = __builtin_amdgcn_exp2f(p1[2 * j]); p1[2 * j + 1] = __builtin_amdgcn_exp2f(p1[2 * j + 1]); sa = fadd_s(sa, p1[2 * j]); sb = fadd_s(sb, p1[2 * j + 1]); }
;         if (j == 3 || j == 7) { const int w = j >> 2;
; #pragma unroll
;             for (int k = 0; k < 4; ++k) pw[2 + w][k] = cvtpk_s(p1[8 * w + 2 * k], p1[8 * w + 2 * k + 1]); }
;         if (j >= 8 && j < 12) dma_piece(dma, j - 8);
;         __builtin_amdgcn_sched_barrier(0);
;     }
;     ...
;     l += sa + sb;
; }
	s_setprio 1
	s_waitcnt lgkmcnt(6)
	v_mfma_f32_32x32x16_bf16 v[0:15], v[96:99], v[104:107], v[0:15]
	v_exp_f32_e32 v80, v80
	ds_read_b64_tr_b16 v[150:151], v147 offset:17408
	ds_read_b64_tr_b16 v[152:153], v147 offset:17920
	v_exp_f32_e32 v81, v81
	v_add_f32_e32 v178, 0, v80
	v_add_f32_e32 v179, 0, v81
	s_waitcnt lgkmcnt(6)
	v_mfma_f32_32x32x16_bf16 v[16:31], v[96:99], v[108:111], v[16:31]
	v_exp_f32_e32 v82, v82
	ds_read_b64_tr_b16 v[174:175], v147 offset:21504
	ds_read_b64_tr_b16 v[176:177], v147 offset:22016
	v_exp_f32_e32 v83, v83
	v_add_f32_e32 v182, v82, v178
	v_add_f32_e32 v183, v83, v179
	s_waitcnt lgkmcnt(6)
	v_mfma_f32_32x32x16_bf16 v[32:47], v[96:99], v[132:135], v[32:47]
	v_exp_f32_e32 v84, v84
	ds_read_b64_tr_b16 v[178:179], v147 offset:25600
	ds_read_b64_tr_b16 v[180:181], v147 offset:26112
	v_exp_f32_e32 v85, v85
	v_add_f32_e32 v186, v84, v182
	v_add_f32_e32 v187, v85, v183
	s_waitcnt lgkmcnt(6)
	v_mfma_f32_32x32x16_bf16 v[48:63], v[96:99], v[128:131], v[48:63]
	v_exp_f32_e32 v86, v86
	ds_read_b64_tr_b16 v[182:183], v147 offset:29696
	ds_read_b64_tr_b16 v[184:185], v147 offset:30208
	v_exp_f32_e32 v87, v87
	v_cvt_pk_bf16_f32 v188, v84, v85
	v_add_f32_e32 v190, v86, v186
	v_add_f32_e32 v191, v87, v187
	v_cvt_pk_bf16_f32 v186, v80, v81
	v_cvt_pk_bf16_f32 v187, v82, v83
	v_cvt_pk_bf16_f32 v189, v86, v87
	s_waitcnt lgkmcnt(6)
	v_mfma_f32_32x32x16_bf16 v[0:15], v[100:103], v[150:153], v[0:15]
	ds_read_b64_tr_b16 v[206:207], v147 offset:18432
	ds_read_b64_tr_b16 v[208:209], v147 offset:18944
	v_exp_f32_e32 v88, v88
	v_exp_f32_e32 v89, v89
	v_add_f32_e32 v190, v88, v190
	v_add_f32_e32 v191, v89, v191
	s_waitcnt lgkmcnt(6)
	v_mfma_f32_32x32x16_bf16 v[16:31], v[100:103], v[174:177], v[16:31]
	ds_read_b64_tr_b16 v[150:151], v147 offset:22528
	ds_read_b64_tr_b16 v[152:153], v147 offset:23040
	v_exp_f32_e32 v90, v90
	v_exp_f32_e32 v91, v91
	v_add_f32_e32 v190, v90, v190
	v_add_f32_e32 v191, v91, v191
	s_waitcnt lgkmcnt(6)
	v_mfma_f32_32x32x16_bf16 v[32:47], v[100:103], v[178:181], v[32:47]
	ds_read_b64_tr_b16 v[174:175], v147 offset:26624
	ds_read_b64_tr_b16 v[176:177], v147 offset:27136
	v_exp_f32_e32 v92, v92
	v_exp_f32_e32 v93, v93
	v_add_f32_e32 v190, v92, v190
	v_add_f32_e32 v191, v93, v191
	s_waitcnt lgkmcnt(6)
	v_mfma_f32_32x32x16_bf16 v[48:63], v[100:103], v[182:185], v[48:63]
	ds_read_b64_tr_b16 v[178:179], v147 offset:30720
	ds_read_b64_tr_b16 v[180:181], v147 offset:31232
	v_exp_f32_e32 v94, v94
	v_exp_f32_e32 v95, v95
	v_cvt_pk_bf16_f32 v182, v88, v89
	v_cvt_pk_bf16_f32 v183, v90, v91
	v_add_f32_e32 v190, v94, v190
	v_add_f32_e32 v191, v95, v191
	v_cvt_pk_bf16_f32 v184, v92, v93
	v_cvt_pk_bf16_f32 v185, v94, v95
	s_setprio 0
	s_waitcnt lgkmcnt(6)
	v_mfma_f32_32x32x16_bf16 v[0:15], v[186:189], v[206:209], v[0:15]
	ds_read_b64_tr_b16 v[210:211], v147 offset:19456
	ds_read_b64_tr_b16 v[212:213], v147 offset:19968
	s_mov_b32 s12, m0
	s_mov_b32 m0, s25
	s_nop 0
	global_load_lds_dwordx4 v[144:145], off
	s_mov_b32 m0, s12
	s_waitcnt lgkmcnt(6)
	v_mfma_f32_32x32x16_bf16 v[16:31], v[186:189], v[150:153], v[16:31]
	ds_read_b64_tr_b16 v[206:207], v147 offset:23552
	ds_read_b64_tr_b16 v[208:209], v147 offset:24064
	v_lshl_add_u64 v[150:151], v[144:145], 0, s[16:17]
	s_add_i32 s12, s25, 0x2000
	s_mov_b32 s13, m0
	s_mov_b32 m0, s12
	s_nop 0
	global_load_lds_dwordx4 v[150:151], off
	s_mov_b32 m0, s13
	s_waitcnt lgkmcnt(6)
	v_mfma_f32_32x32x16_bf16 v[32:47], v[186:189], v[174:177], v[32:47]
	ds_read_b64_tr_b16 v[150:151], v147 offset:27648
	ds_read_b64_tr_b16 v[152:153], v147 offset:28160
	s_mov_b32 s12, m0
	s_mov_b32 m0, s24
	s_nop 0
	global_load_lds_dwordx4 v[148:149], off
	s_mov_b32 m0, s12
	s_waitcnt lgkmcnt(6)
	v_mfma_f32_32x32x16_bf16 v[48:63], v[186:189], v[178:181], v[48:63]
	ds_read_b64_tr_b16 v[174:175], v147 offset:31744
	ds_read_b64_tr_b16 v[176:177], v147 offset:32256
	v_lshl_add_u64 v[178:179], v[148:149], 0, s[0:1]
	s_add_i32 s12, s24, 0x400
	s_mov_b32 s13, m0
	s_mov_b32 m0, s12
	s_nop 0
	global_load_lds_dwordx4 v[178:179], off
	s_mov_b32 m0, s13
	s_waitcnt lgkmcnt(6)
	v_mfma_f32_32x32x16_bf16 v[0:15], v[182:185], v[210:213], v[0:15]
	s_waitcnt lgkmcnt(4)
	v_mfma_f32_32x32x16_bf16 v[16:31], v[182:185], v[206:209], v[16:31]
	s_waitcnt lgkmcnt(2)
	v_mfma_f32_32x32x16_bf16 v[32:47], v[182:185], v[150:153], v[32:47]
	s_waitcnt lgkmcnt(0)
	v_mfma_f32_32x32x16_bf16 v[48:63], v[182:185], v[174:177], v[48:63]
	s_add_i32 s12, s54, 0x8000
	s_waitcnt vmcnt(8) lgkmcnt(0)
	s_barrier
	s_cmp_lg_u32 s54, 0x18000
	v_add_f32_e32 v147, v190, v191
	s_cselect_b32 s54, s12, 0
	s_add_i32 s19, s19, -1
	v_lshl_add_u64 v[144:145], v[144:145], 0, s[42:43]
	v_lshl_add_u64 v[148:149], v[148:149], 0, s[42:43]
	s_cmp_eq_u32 s19, 0
	v_add_f32_e32 v173, v173, v147
	s_cbranch_scc0 .LBB0_93
	s_add_i32 s55, s66, -1
	s_cmp_ge_i32 s55, s70
	s_cbranch_scc0 .LBB0_96
	s_branch .LBB0_112

; #define LAS __attribute__((address_space(3)))
; __device__ __forceinline__ unsigned cvt_pk_bf16(float lo, float hi) { f32x2 v = {lo, hi}; bf16x2_t b = __builtin_convertvector(v, bf16x2_t); return __builtin_bit_cast(unsigned, b); }
; __device__ __forceinline__ float bf_lo(unsigned w) { return __uint_as_float(w << 16); }
; __device__ __forceinline__ float bf_hi(unsigned w) { return __uint_as_float(w & 0xffff0000u); }
; __device__ __forceinline__ void sgu_chunk(const Ctx& C, const Args& a, int l, int n) {
;     ...
;     for (int g = 0; g < 8; ++g) {
; #pragma unroll
;         for (int j = 0; j < 4; ++j) { const int p = C.tid + 512 * j, r = p >> 4, c8 = (p & 15) * 8; const f32x2 st = stats[r];
;             const u32x4 w = *(const u32x4*)(VB + (R0 + r) * D + g * 128 + c8); const f32x4 g0 = *(const f32x4*)(gam + g * 128 + c8), g1 = *(const f32x4*)(gam + g * 128 + c8 + 4);
;             const f32x4 b0 = *(const f32x4*)(bet + g * 128 + c8), b1 = *(const f32x4*)(bet + g * 128 + c8 + 4);
;             u32x4 o; o.x = cvt_pk_bf16((bf_lo(w.x) - st.x) * st.y * g0[0] + b0[0], (bf_hi(w.x) - st.x) * st.y * g0[1] + b0[1]);
;             o.y = cvt_pk_bf16((bf_lo(w.y) - st.x) * st.y * g0[2] + b0[2], (bf_hi(w.y) - st.x) * st.y * g0[3] + b0[3]);
;             o.z = cvt_pk_bf16((bf_lo(w.z) - st.x) * st.y * g1[0] + b1[0], (bf_hi(w.z) - st.x) * st.y * g1[1] + b1[1]);
;             o.w = cvt_pk_bf16((bf_lo(w.w) - st.x) * st.y * g1[2] + b1[2], (bf_hi(w.w) - st.x) * st.y * g1[3] + b1[3]);
;             *(LAS u32x4*)(vimg + (c8 >> 5) * 8192 + r * 64 + (c8 & 31) * 2) = o; }
;         __syncthreads();
.LBB0_154:
	v_lshl_add_u64 v[78:79], s[86:87], 0, v[56:57]
	global_load_dwordx2 v[206:207], v[78:79], off offset:-128
	global_load_dwordx2 v[208:209], v[78:79], off offset:-112
	global_load_dwordx2 v[210:211], v[78:79], off offset:-96
	global_load_dwordx2 v[212:213], v[78:79], off offset:-80
	global_load_dwordx2 v[214:215], v[78:79], off offset:-64
	global_load_dwordx2 v[216:217], v[78:79], off offset:-48
	global_load_dwordx2 v[218:219], v[78:79], off offset:-32
	global_load_dwordx2 v[220:221], v[78:79], off offset:-16
	global_load_dwordx2 v[232:233], v[78:79], off offset:0
	global_load_dwordx2 v[234:235], v[78:79], off offset:16
	global_load_dwordx2 v[236:237], v[78:79], off offset:32
	global_load_dwordx2 v[238:239], v[78:79], off offset:48
	global_load_dwordx2 v[240:241], v[78:79], off offset:64
	global_load_dwordx2 v[242:243], v[78:79], off offset:80
	global_load_dwordx2 v[244:245], v[78:79], off offset:96
	global_load_dwordx2 v[246:247], v[78:79], off offset:112
	v_lshl_add_u64 v[176:177], s[86:87], 0, v[62:63]
	global_load_dwordx4 v[164:167], v[176:177], off
	v_lshl_add_u64 v[176:177], s[86:87], 0, v[60:61]
	global_load_dwordx4 v[168:171], v[176:177], off
	v_lshl_add_u64 v[176:177], s[86:87], 0, v[58:59]
	global_load_dwordx4 v[172:175], v[176:177], off
	v_lshl_add_u64 v[0:1], s[86:87], 0, v[64:65]
	global_load_dwordx4 v[16:19], v[0:1], off
	v_lshl_add_u64 v[0:1], v[52:53], 0, s[44:45]
	v_lshl_add_u64 v[8:9], v[54:55], 0, s[44:45]
	ds_read_b64 v[20:21], v68
	global_load_dwordx4 v[4:7], v[0:1], off offset:-16
	s_nop 0
	global_load_dwordx4 v[0:3], v[0:1], off
	s_nop 0
	global_load_dwordx4 v[12:15], v[8:9], off offset:-16
	s_nop 0
	global_load_dwordx4 v[8:11], v[8:9], off
	s_add_u32 s18, s24, s44
	s_addc_u32 s19, s25, s45
	s_mov_b32 s12, 0x5c00000
	v_lshl_add_u64 v[64:65], v[64:65], 0, s[14:15]
	v_lshl_add_u64 v[56:57], v[56:57], 0, s[94:95]
	s_waitcnt vmcnt(4)
	v_lshlrev_b32_e32 v22, 16, v16
	v_and_b32_e32 v23, 0xffff0000, v16
	s_waitcnt lgkmcnt(0)
	v_pk_add_f32 v[22:23], v[22:23], v[20:21] op_sel_hi:[1,0] neg_lo:[0,1] neg_hi:[0,1]
	s_nop 0
	v_pk_mul_f32 v[22:23], v[20:21], v[22:23] op_sel:[1,0]
	s_waitcnt vmcnt(1)
	v_pk_fma_f32 v[22:23], v[4:5], v[22:23], v[12:13]
	s_nop 0
	v_cvt_pk_bf16_f32 v16, v22, v23
	v_lshlrev_b32_e32 v22, 16, v17
	v_and_b32_e32 v23, 0xffff0000, v17
	v_pk_add_f32 v[22:23], v[22:23], v[20:21] op_sel_hi:[1,0] neg_lo:[0,1] neg_hi:[0,1]
	s_nop 0
	v_pk_mul_f32 v[22:23], v[20:21], v[22:23] op_sel:[1,0]
	s_nop 0
	v_pk_fma_f32 v[22:23], v[6:7], v[22:23], v[14:15]
	s_nop 0
	v_cvt_pk_bf16_f32 v17, v22, v23
	v_lshlrev_b32_e32 v22, 16, v18
	v_and_b32_e32 v23, 0xffff0000, v18
	v_pk_add_f32 v[22:23], v[22:23], v[20:21] op_sel_hi:[1,0] neg_lo:[0,1] neg_hi:[0,1]
	s_nop 0
	v_pk_mul_f32 v[22:23], v[20:21], v[22:23] op_sel:[1,0]
	s_waitcnt vmcnt(0)
	v_pk_fma_f32 v[22:23], v[0:1], v[22:23], v[8:9]
	s_nop 0
	v_cvt_pk_bf16_f32 v18, v22, v23
	v_lshlrev_b32_e32 v22, 16, v19
	v_and_b32_e32 v23, 0xffff0000, v19
	v_pk_add_f32 v[22:23], v[22:23], v[20:21] op_sel_hi:[1,0] neg_lo:[0,1] neg_hi:[0,1]
	s_nop 0
	v_pk_mul_f32 v[20:21], v[20:21], v[22:23] op_sel:[1,0]
	s_nop 0
	v_pk_fma_f32 v[20:21], v[2:3], v[20:21], v[10:11]
	s_nop 0
	v_cvt_pk_bf16_f32 v19, v20, v21
	ds_write_b128 v72, v[16:19] offset:1024
	v_mov_b32_e32 v16, v164
	v_mov_b32_e32 v17, v165
	v_mov_b32_e32 v18, v166
	v_mov_b32_e32 v19, v167
	ds_read_b64 v[20:21], v69
	v_lshl_add_u64 v[62:63], v[62:63], 0, s[14:15]
	s_waitcnt vmcnt(0)
	v_lshlrev_b32_e32 v22, 16, v16
	v_and_b32_e32 v23, 0xffff0000, v16
	s_waitcnt lgkmcnt(0)
	v_pk_add_f32 v[22:23], v[22:23], v[20:21] op_sel_hi:[1,0] neg_lo:[0,1] neg_hi:[0,1]
	s_nop 0
	v_pk_mul_f32 v[22:23], v[20:21], v[22:23] op_sel:[1,0]
	s_nop 0
	v_pk_fma_f32 v[22:23], v[4:5], v[22:23], v[12:13]
	s_nop 0
	v_cvt_pk_bf16_f32 v16, v22, v23
	v_lshlrev_b32_e32 v22, 16, v17
	v_and_b32_e32 v23, 0xffff0000, v17
	v_pk_add_f32 v[22:23], v[22:23], v[20:21] op_sel_hi:[1,0] neg_lo:[0,1] neg_hi:[0,1]
	s_nop 0
	v_pk_mul_f32 v[22:23], v[20:21], v[22:23] op_sel:[1,0]
	s_nop 0
	v_pk_fma_f32 v[22:23], v[6:7], v[22:23], v[14:15]
	s_nop 0
	v_cvt_pk_bf16_f32 v17, v22, v23
	v_lshlrev_b32_e32 v22, 16, v18
	v_and_b32_e32 v23, 0xffff0000, v18
	v_pk_add_f32 v[22:23], v[22:23], v[20:21] op_sel_hi:[1,0] neg_lo:[0,1] neg_hi:[0,1]
	s_nop 0
	v_pk_mul_f32 v[22:23], v[20:21], v[22:23] op_sel:[1,0]
	s_nop 0
	v_pk_fma_f32 v[22:23], v[0:1], v[22:23], v[8:9]
	s_nop 0
	v_cvt_pk_bf16_f32 v18, v22, v23
	v_lshlrev_b32_e32 v22, 16, v19
	v_and_b32_e32 v23, 0xffff0000, v19
	v_pk_add_f32 v[22:23], v[22:23], v[20:21] op_sel_hi:[1,0] neg_lo:[0,1] neg_hi:[0,1]
	s_nop 0
	v_pk_mul_f32 v[20:21], v[20:21], v[22:23] op_sel:[1,0]
	s_nop 0
	v_pk_fma_f32 v[20:21], v[2:3], v[20:21], v[10:11]
	s_nop 0
	v_cvt_pk_bf16_f32 v19, v20, v21
	ds_write_b128 v73, v[16:19] offset:1024
	v_mov_b32_e32 v16, v168
	v_mov_b32_e32 v17, v169
	v_mov_b32_e32 v18, v170
	v_mov_b32_e32 v19, v171
	ds_read_b64 v[20:21], v70
	v_lshl_add_u64 v[60:61], v[60:61], 0, s[14:15]
	s_waitcnt vmcnt(0)
	v_lshlrev_b32_e32 v22, 16, v16
	v_and_b32_e32 v23, 0xffff0000, v16
	s_waitcnt lgkmcnt(0)
; #define LAS __attribute__((address_space(3)))
; __device__ __forceinline__ unsigned cvt_pk_bf16(float lo, float hi) { f32x2 v = {lo, hi}; bf16x2_t b = __builtin_convertvector(v, bf16x2_t); return __builtin_bit_cast(unsigned, b); }
; __device__ __forceinline__ float bf_lo(unsigned w) { return __uint_as_float(w << 16); }
; __device__ __forceinline__ float bf_hi(unsigned w) { return __uint_as_float(w & 0xffff0000u); }
; __device__ __forceinline__ void sgu_chunk(const Ctx& C, const Args& a, int l, int n) {
;     ...
;         for (int j = 0; j < 4; ++j) { const int p = C.tid + 512 * j, r = p >> 4, c8 = (p & 15) * 8; const f32x2 st = stats[r];
;             const u32x4 w = *(const u32x4*)(VB + (R0 + r) * D + g * 128 + c8); const f32x4 g0 = *(const f32x4*)(gam + g * 128 + c8), g1 = *(const f32x4*)(gam + g * 128 + c8 + 4);
;             const f32x4 b0 = *(const f32x4*)(bet + g * 128 + c8), b1 = *(const f32x4*)(bet + g * 128 + c8 + 4);
;             u32x4 o; o.x = cvt_pk_bf16((bf_lo(w.x) - st.x) * st.y * g0[0] + b0[0], (bf_hi(w.x) - st.x) * st.y * g0[1] + b0[1]);
;             o.y = cvt_pk_bf16((bf_lo(w.y) - st.x) * st.y * g0[2] + b0[2], (bf_hi(w.y) - st.x) * st.y * g0[3] + b0[3]);
;             o.z = cvt_pk_bf16((bf_lo(w.z) - st.x) * st.y * g1[0] + b1[0], (bf_hi(w.z) - st.x) * st.y * g1[1] + b1[1]);
;             o.w = cvt_pk_bf16((bf_lo(w.w) - st.x) * st.y * g1[2] + b1[2], (bf_hi(w.w) - st.x) * st.y * g1[3] + b1[3]);
;             *(LAS u32x4*)(vimg + (c8 >> 5) * 8192 + r * 64 + (c8 & 31) * 2) = o; }
;         __syncthreads();
;         f32x16 acc[2];
; #pragma unroll
;         for (int r = 0; r < 16; ++r) { acc[0][r] = 0.f; acc[1][r] = 0.f; }
;         const bf16_t* wrow = SW + ((size_t)g * 128 + 32 * tb + r32) * 128 + 4 * hi;
; #pragma unroll
;         for (int kc = 0; kc < 8; ++kc) {
;             const u32x2 alo = *(const u32x2*)(wrow + 16 * kc), ahi = *(const u32x2*)(wrow + 16 * kc + 8);
;             const bf16x8 af = __builtin_bit_cast(bf16x8, (u32x4){alo.x, alo.y, ahi.x, ahi.y});
; #pragma unroll
;             for (int j = 0; j < 2; ++j) { LAS const unsigned char* vp = vimg + (2 * ch + j) * 8192 + kc * 1024 + voff; const s16x4 lo = att::vtr(vp), hh = att::vtr(vp + 512);
;                 const bf16x8 vf = (bf16x8){lo[0], lo[1], lo[2], lo[3], hh[0], hh[1], hh[2], hh[3]}; acc[j] = ATT_MFMA(af, vf, acc[j]); }
;         }
	v_pk_add_f32 v[22:23], v[22:23], v[20:21] op_sel_hi:[1,0] neg_lo:[0,1] neg_hi:[0,1]
	s_nop 0
	v_pk_mul_f32 v[22:23], v[20:21], v[22:23] op_sel:[1,0]
	s_nop 0
	v_pk_fma_f32 v[22:23], v[4:5], v[22:23], v[12:13]
	s_nop 0
	v_cvt_pk_bf16_f32 v16, v22, v23
	v_lshlrev_b32_e32 v22, 16, v17
	v_and_b32_e32 v23, 0xffff0000, v17
	v_pk_add_f32 v[22:23], v[22:23], v[20:21] op_sel_hi:[1,0] neg_lo:[0,1] neg_hi:[0,1]
	s_nop 0
	v_pk_mul_f32 v[22:23], v[20:21], v[22:23] op_sel:[1,0]
	s_nop 0
	v_pk_fma_f32 v[22:23], v[6:7], v[22:23], v[14:15]
	s_nop 0
	v_cvt_pk_bf16_f32 v17, v22, v23
	v_lshlrev_b32_e32 v22, 16, v18
	v_and_b32_e32 v23, 0xffff0000, v18
	v_pk_add_f32 v[22:23], v[22:23], v[20:21] op_sel_hi:[1,0] neg_lo:[0,1] neg_hi:[0,1]
	s_nop 0
	v_pk_mul_f32 v[22:23], v[20:21], v[22:23] op_sel:[1,0]
	s_nop 0
	v_pk_fma_f32 v[22:23], v[0:1], v[22:23], v[8:9]
	s_nop 0
	v_cvt_pk_bf16_f32 v18, v22, v23
	v_lshlrev_b32_e32 v22, 16, v19
	v_and_b32_e32 v23, 0xffff0000, v19
	v_pk_add_f32 v[22:23], v[22:23], v[20:21] op_sel_hi:[1,0] neg_lo:[0,1] neg_hi:[0,1]
	s_nop 0
	v_pk_mul_f32 v[20:21], v[20:21], v[22:23] op_sel:[1,0]
	s_nop 0
	v_pk_fma_f32 v[20:21], v[2:3], v[20:21], v[10:11]
	s_nop 0
	v_cvt_pk_bf16_f32 v19, v20, v21
	ds_write_b128 v74, v[16:19] offset:1024
	v_mov_b32_e32 v16, v172
	v_mov_b32_e32 v17, v173
	v_mov_b32_e32 v18, v174
	v_mov_b32_e32 v19, v175
	ds_read_b64 v[20:21], v71
	v_lshl_add_u64 v[58:59], v[58:59], 0, s[14:15]
	s_waitcnt vmcnt(0)
	v_lshlrev_b32_e32 v22, 16, v16
	v_and_b32_e32 v23, 0xffff0000, v16
	s_waitcnt lgkmcnt(0)
	v_pk_add_f32 v[22:23], v[22:23], v[20:21] op_sel_hi:[1,0] neg_lo:[0,1] neg_hi:[0,1]
	s_nop 0
	v_pk_mul_f32 v[22:23], v[20:21], v[22:23] op_sel:[1,0]
	s_nop 0
	v_pk_fma_f32 v[4:5], v[4:5], v[22:23], v[12:13]
	v_lshlrev_b32_e32 v12, 16, v17
	v_and_b32_e32 v13, 0xffff0000, v17
	v_pk_add_f32 v[12:13], v[12:13], v[20:21] op_sel_hi:[1,0] neg_lo:[0,1] neg_hi:[0,1]
	v_cvt_pk_bf16_f32 v4, v4, v5
	v_pk_mul_f32 v[12:13], v[20:21], v[12:13] op_sel:[1,0]
	s_nop 0
	v_pk_fma_f32 v[6:7], v[6:7], v[12:13], v[14:15]
	s_nop 0
	v_cvt_pk_bf16_f32 v5, v6, v7
	v_lshlrev_b32_e32 v6, 16, v18
	v_and_b32_e32 v7, 0xffff0000, v18
	v_pk_add_f32 v[6:7], v[6:7], v[20:21] op_sel_hi:[1,0] neg_lo:[0,1] neg_hi:[0,1]
	s_nop 0
	v_pk_mul_f32 v[6:7], v[20:21], v[6:7] op_sel:[1,0]
	s_nop 0
	v_pk_fma_f32 v[0:1], v[0:1], v[6:7], v[8:9]
	s_nop 0
	v_cvt_pk_bf16_f32 v6, v0, v1
	v_lshlrev_b32_e32 v0, 16, v19
	v_and_b32_e32 v1, 0xffff0000, v19
	v_pk_add_f32 v[0:1], v[0:1], v[20:21] op_sel_hi:[1,0] neg_lo:[0,1] neg_hi:[0,1]
	s_nop 0
	v_pk_mul_f32 v[0:1], v[20:21], v[0:1] op_sel:[1,0]
	s_nop 0
	v_pk_fma_f32 v[0:1], v[2:3], v[0:1], v[10:11]
	s_nop 0
	v_cvt_pk_bf16_f32 v7, v0, v1
	ds_write_b128 v75, v[4:7] offset:1024
	s_waitcnt lgkmcnt(0)
	s_barrier
	ds_read_b64_tr_b16 v[4:5], v76 offset:1024
	ds_read_b64_tr_b16 v[6:7], v76 offset:1536
	s_waitcnt vmcnt(0) lgkmcnt(0)
	v_mfma_f32_32x32x16_bf16 v[16:31], v[206:209], v[4:7], 0
	ds_read_b64_tr_b16 v[4:5], v76 offset:9216
	ds_read_b64_tr_b16 v[6:7], v76 offset:9728
	ds_read_b64_tr_b16 v[36:37], v76 offset:2048
	ds_read_b64_tr_b16 v[38:39], v76 offset:2560
	s_waitcnt lgkmcnt(2)
	v_mfma_f32_32x32x16_bf16 v[0:15], v[206:209], v[4:7], 0
	s_waitcnt vmcnt(0) lgkmcnt(0)
	v_mfma_f32_32x32x16_bf16 v[16:31], v[210:213], v[36:39], v[16:31]
	ds_read_b64_tr_b16 v[36:37], v76 offset:10240
	ds_read_b64_tr_b16 v[38:39], v76 offset:10752
	s_waitcnt lgkmcnt(0)
	v_mfma_f32_32x32x16_bf16 v[0:15], v[210:213], v[36:39], v[0:15]
	ds_read_b64_tr_b16 v[36:37], v76 offset:3072
	ds_read_b64_tr_b16 v[38:39], v76 offset:3584
	s_waitcnt vmcnt(0) lgkmcnt(0)
	v_mfma_f32_32x32x16_bf16 v[16:31], v[214:217], v[36:39], v[16:31]
	ds_read_b64_tr_b16 v[36:37], v76 offset:11264
	ds_read_b64_tr_b16 v[38:39], v76 offset:11776
	s_waitcnt lgkmcnt(0)
	v_mfma_f32_32x32x16_bf16 v[0:15], v[214:217], v[36:39], v[0:15]
	ds_read_b64_tr_b16 v[36:37], v76 offset:4096
	ds_read_b64_tr_b16 v[38:39], v76 offset:4608
	s_waitcnt vmcnt(0) lgkmcnt(0)
	v_mfma_f32_32x32x16_bf16 v[16:31], v[218:221], v[36:39], v[16:31]
	ds_read_b64_tr_b16 v[36:37], v76 offset:12288
	ds_read_b64_tr_b16 v[38:39], v76 offset:12800
	s_waitcnt lgkmcnt(0)
	v_mfma_f32_32x32x16_bf16 v[0:15], v[218:221], v[36:39], v[0:15]
	ds_read_b64_tr_b16 v[36:37], v76 offset:5120
	ds_read_b64_tr_b16 v[38:39], v76 offset:5632
	s_waitcnt vmcnt(0) lgkmcnt(0)
	v_mfma_f32_32x32x16_bf16 v[16:31], v[232:235], v[36:39], v[16:31]
	ds_read_b64_tr_b16 v[36:37], v76 offset:13312
	ds_read_b64_tr_b16 v[38:39], v76 offset:13824
	s_waitcnt lgkmcnt(0)
	v_mfma_f32_32x32x16_bf16 v[0:15], v[232:235], v[36:39], v[0:15]
	ds_read_b64_tr_b16 v[36:37], v76 offset:6144
	ds_read_b64_tr_b16 v[38:39], v76 offset:6656
	s_waitcnt vmcnt(0) lgkmcnt(0)
	v_mfma_f32_32x32x16_bf16 v[16:31], v[236:239], v[36:39], v[16:31]
	ds_read_b64_tr_b16 v[36:37], v76 offset:14336
	ds_read_b64_tr_b16 v[38:39], v76 offset:14848
	s_waitcnt lgkmcnt(0)
	v_mfma_f32_32x32x16_bf16 v[0:15], v[236:239], v[36:39], v[0:15]
	ds_read_b64_tr_b16 v[36:37], v76 offset:7168
	ds_read_b64_tr_b16 v[38:39], v76 offset:7680
	s_waitcnt vmcnt(0) lgkmcnt(0)
	v_mfma_f32_32x32x16_bf16 v[16:31], v[240:243], v[36:39], v[16:31]
	ds_read_b64_tr_b16 v[36:37], v76 offset:15360
	ds_read_b64_tr_b16 v[38:39], v76 offset:15872
	s_waitcnt lgkmcnt(0)
	v_mfma_f32_32x32x16_bf16 v[0:15], v[240:243], v[36:39], v[0:15]
	ds_read_b64_tr_b16 v[36:37], v76 offset:8192
	ds_read_b64_tr_b16 v[38:39], v76 offset:8704
	s_waitcnt vmcnt(0) lgkmcnt(0)
	v_mfma_f32_32x32x16_bf16 v[16:31], v[244:247], v[36:39], v[16:31]
	ds_read_b64_tr_b16 v[36:37], v76 offset:16384
	ds_read_b64_tr_b16 v[38:39], v76 offset:16896
	s_waitcnt lgkmcnt(0)
; __device__ __forceinline__ unsigned cvt_pk_bf16(float lo, float hi) { f32x2 v = {lo, hi}; bf16x2_t b = __builtin_convertvector(v, bf16x2_t); return __builtin_bit_cast(unsigned, b); }
; __device__ __forceinline__ int crow(int r, int hi) { return (r & 3) + 8 * (r >> 2) + 4 * hi; }
; __device__ __forceinline__ void sgu_chunk(const Ctx& C, const Args& a, int l, int n) {
;     ...
;         int hi_e = hi, r32_e = r32; asm volatile("" : "+v"(hi_e), "+v"(r32_e));
;         const float* sbp = sb + g * 128 + 32 * tb + 4 * hi_e; bf16_t* hp = HC + (R0 + 32 * tb + 4 * hi_e) * 2048 + g * 128 + 64 * ch + r32_e;
;         bf16_t uu[16][2]; float bsv[16];
; #pragma unroll
;         for (int r = 0; r < 16; ++r) { bsv[r] = sbp[att::crow(r, 0)];
; #pragma unroll
;             for (int j = 0; j < 2; ++j) uu[r][j] = hp[att::crow(r, 0) * 2048 + 32 * j]; }
;         asm volatile("" ::: "memory");
; #pragma unroll
;         for (int r = 0; r < 16; ++r)
; #pragma unroll
;             for (int j = 0; j < 2; ++j) { const float u = __uint_as_float((unsigned)uu[r][j] << 16);
;                 hp[att::crow(r, 0) * 2048 + 32 * j] = (bf16_t)(cvt_pk_bf16(u * (acc[j][r] + bsv[r]), 0.f) & 0xffffu); }
	v_mfma_f32_32x32x16_bf16 v[0:15], v[244:247], v[36:39], v[0:15]
	v_mov_b32_e32 v32, v66
	v_mov_b32_e32 v33, v67
	s_nop 0
	v_lshlrev_b32_e32 v34, 2, v33
	v_ashrrev_i32_e32 v35, 31, v34
	v_lshl_add_u64 v[86:87], v[34:35], 2, s[18:19]
	v_lshl_add_u64 v[34:35], s[40:41], 0, v[34:35]
	v_ashrrev_i32_e32 v33, 31, v32
	v_lshlrev_b64 v[34:35], 12, v[34:35]
	s_add_u32 s18, s86, s46
	v_lshl_add_u64 v[32:33], v[32:33], 1, v[34:35]
	s_addc_u32 s19, s87, s47
	v_lshl_add_u64 v[88:89], s[18:19], 0, v[32:33]
	global_load_dwordx4 v[78:81], v[86:87], off
	global_load_dwordx4 v[82:85], v[86:87], off offset:32
	global_load_dwordx4 v[36:39], v[86:87], off offset:64
	global_load_dwordx4 v[32:35], v[86:87], off offset:96
	v_lshrrev_b32_e32 v90, 1, v230
	v_lshlrev_b32_e32 v91, 2, v67
	v_sub_u32_e32 v90, v90, v91
	v_lshlrev_b32_e32 v90, 12, v90
	v_and_b32_e32 v91, 1, v230
	v_lshl_add_u32 v90, v91, 6, v90
	v_lshlrev_b32_e32 v91, 1, v66
	v_sub_u32_e32 v90, v90, v91
	v_add_u32_e32 v90, 0x5c00000, v90
	v_mov_b32_e32 v91, 0
	v_lshl_add_u64 v[92:93], v[88:89], 0, v[90:91]
	global_load_dwordx4 v[128:131], v[92:93], off
	global_load_dwordx4 v[132:135], v[92:93], off offset:16
	global_load_dwordx4 v[136:139], v[92:93], off offset:32
	global_load_dwordx4 v[140:143], v[92:93], off offset:48
	v_lshrrev_b32_e32 v94, 6, v231
	v_mul_u32_u24_e32 v94, 0x2200, v94
	v_add_u32_e32 v94, 0x9000, v94
	v_mul_u32_u24_e32 v95, 0x440, v67
	v_lshl_add_u32 v95, v66, 2, v95
	v_lshrrev_b32_e32 v90, 1, v230
	v_mul_u32_u24_e32 v90, 0x110, v90
	v_and_b32_e32 v91, 1, v230
	v_lshl_add_u32 v90, v91, 7, v90
	v_add_u32_e32 v95, v94, v95
	v_add_u32_e32 v94, v94, v90
	s_waitcnt vmcnt(4)
	v_add_f32_e32 v16, v16, v78
	v_add_f32_e32 v0, v0, v78
	v_add_f32_e32 v17, v17, v79
	v_add_f32_e32 v1, v1, v79
	v_add_f32_e32 v18, v18, v80
	v_add_f32_e32 v2, v2, v80
	v_add_f32_e32 v19, v19, v81
	v_add_f32_e32 v3, v3, v81
	v_add_f32_e32 v20, v20, v82
	v_add_f32_e32 v4, v4, v82
	v_add_f32_e32 v21, v21, v83
	v_add_f32_e32 v5, v5, v83
	v_add_f32_e32 v22, v22, v84
	v_add_f32_e32 v6, v6, v84
	v_add_f32_e32 v23, v23, v85
	v_add_f32_e32 v7, v7, v85
	v_add_f32_e32 v24, v24, v36
	v_add_f32_e32 v8, v8, v36
	v_add_f32_e32 v25, v25, v37
	v_add_f32_e32 v9, v9, v37
	v_add_f32_e32 v26, v26, v38
	v_add_f32_e32 v10, v10, v38
	v_add_f32_e32 v27, v27, v39
	v_add_f32_e32 v11, v11, v39
	v_add_f32_e32 v28, v28, v32
	v_add_f32_e32 v12, v12, v32
	v_add_f32_e32 v29, v29, v33
	v_add_f32_e32 v13, v13, v33
	v_add_f32_e32 v30, v30, v34
	v_add_f32_e32 v14, v14, v34
	v_add_f32_e32 v31, v31, v35
	v_add_f32_e32 v15, v15, v35
	ds_write_b32 v95, v16
	ds_write_b32 v95, v0 offset:128
	ds_write_b32 v95, v17 offset:272
	ds_write_b32 v95, v1 offset:400
	ds_write_b32 v95, v18 offset:544
	ds_write_b32 v95, v2 offset:672
	ds_write_b32 v95, v19 offset:816
	ds_write_b32 v95, v3 offset:944
	ds_write_b32 v95, v20 offset:2176
	ds_write_b32 v95, v4 offset:2304
	ds_write_b32 v95, v21 offset:2448
	ds_write_b32 v95, v5 offset:2576
	ds_write_b32 v95, v22 offset:2720
	ds_write_b32 v95, v6 offset:2848
	ds_write_b32 v95, v23 offset:2992
	ds_write_b32 v95, v7 offset:3120
	ds_write_b32 v95, v24 offset:4352
	ds_write_b32 v95, v8 offset:4480
	ds_write_b32 v95, v25 offset:4624
	ds_write_b32 v95, v9 offset:4752
	ds_write_b32 v95, v26 offset:4896
	ds_write_b32 v95, v10 offset:5024
	ds_write_b32 v95, v27 offset:5168
	ds_write_b32 v95, v11 offset:5296
	ds_write_b32 v95, v28 offset:6528
	ds_write_b32 v95, v12 offset:6656
	ds_write_b32 v95, v29 offset:6800
	ds_write_b32 v95, v13 offset:6928
	ds_write_b32 v95, v30 offset:7072
	ds_write_b32 v95, v14 offset:7200
	ds_write_b32 v95, v31 offset:7344
	ds_write_b32 v95, v15 offset:7472
	s_waitcnt lgkmcnt(0)
; __device__ __forceinline__ unsigned cvt_pk_bf16(float lo, float hi) { f32x2 v = {lo, hi}; bf16x2_t b = __builtin_convertvector(v, bf16x2_t); return __builtin_bit_cast(unsigned, b); }
; __device__ __forceinline__ int crow(int r, int hi) { return (r & 3) + 8 * (r >> 2) + 4 * hi; }
; __device__ __forceinline__ void sgu_chunk(const Ctx& C, const Args& a, int l, int n) {
;     ...
; #pragma unroll
;         for (int r = 0; r < 16; ++r)
; #pragma unroll
;             for (int j = 0; j < 2; ++j) { const float u = __uint_as_float((unsigned)uu[r][j] << 16);
;                 hp[att::crow(r, 0) * 2048 + 32 * j] = (bf16_t)(cvt_pk_bf16(u * (acc[j][r] + bsv[r]), 0.f) & 0xffffu); }
;         __syncthreads();
	ds_read_b128 v[96:99], v94
	ds_read_b128 v[100:103], v94 offset:16
	ds_read_b128 v[104:107], v94 offset:32
	ds_read_b128 v[108:111], v94 offset:48
	ds_read_b128 v[112:115], v94 offset:64
	ds_read_b128 v[116:119], v94 offset:80
	ds_read_b128 v[120:123], v94 offset:96
	ds_read_b128 v[124:127], v94 offset:112
	s_waitcnt vmcnt(0) lgkmcnt(0)
	v_lshlrev_b32_e32 v144, 16, v128
	v_and_b32_e32 v145, 0xffff0000, v128
	v_mul_f32_e32 v144, v144, v96
	v_mul_f32_e32 v145, v145, v97
	v_cvt_pk_bf16_f32 v128, v144, v145
	v_lshlrev_b32_e32 v146, 16, v129
	v_and_b32_e32 v147, 0xffff0000, v129
	v_mul_f32_e32 v146, v146, v98
	v_mul_f32_e32 v147, v147, v99
	v_cvt_pk_bf16_f32 v129, v146, v147
	v_lshlrev_b32_e32 v144, 16, v130
	v_and_b32_e32 v145, 0xffff0000, v130
	v_mul_f32_e32 v144, v144, v100
	v_mul_f32_e32 v145, v145, v101
	v_cvt_pk_bf16_f32 v130, v144, v145
	v_lshlrev_b32_e32 v146, 16, v131
	v_and_b32_e32 v147, 0xffff0000, v131
	v_mul_f32_e32 v146, v146, v102
	v_mul_f32_e32 v147, v147, v103
	v_cvt_pk_bf16_f32 v131, v146, v147
	v_lshlrev_b32_e32 v144, 16, v132
	v_and_b32_e32 v145, 0xffff0000, v132
	v_mul_f32_e32 v144, v144, v104
	v_mul_f32_e32 v145, v145, v105
	v_cvt_pk_bf16_f32 v132, v144, v145
	v_lshlrev_b32_e32 v146, 16, v133
	v_and_b32_e32 v147, 0xffff0000, v133
	v_mul_f32_e32 v146, v146, v106
	v_mul_f32_e32 v147, v147, v107
	v_cvt_pk_bf16_f32 v133, v146, v147
	v_lshlrev_b32_e32 v144, 16, v134
	v_and_b32_e32 v145, 0xffff0000, v134
	v_mul_f32_e32 v144, v144, v108
	v_mul_f32_e32 v145, v145, v109
	v_cvt_pk_bf16_f32 v134, v144, v145
	v_lshlrev_b32_e32 v146, 16, v135
	v_and_b32_e32 v147, 0xffff0000, v135
	v_mul_f32_e32 v146, v146, v110
	v_mul_f32_e32 v147, v147, v111
	v_cvt_pk_bf16_f32 v135, v146, v147
	v_lshlrev_b32_e32 v144, 16, v136
	v_and_b32_e32 v145, 0xffff0000, v136
	v_mul_f32_e32 v144, v144, v112
	v_mul_f32_e32 v145, v145, v113
	v_cvt_pk_bf16_f32 v136, v144, v145
	v_lshlrev_b32_e32 v146, 16, v137
	v_and_b32_e32 v147, 0xffff0000, v137
	v_mul_f32_e32 v146, v146, v114
	v_mul_f32_e32 v147, v147, v115
	v_cvt_pk_bf16_f32 v137, v146, v147
	v_lshlrev_b32_e32 v144, 16, v138
	v_and_b32_e32 v145, 0xffff0000, v138
	v_mul_f32_e32 v144, v144, v116
	v_mul_f32_e32 v145, v145, v117
	v_cvt_pk_bf16_f32 v138, v144, v145
	v_lshlrev_b32_e32 v146, 16, v139
	v_and_b32_e32 v147, 0xffff0000, v139
	v_mul_f32_e32 v146, v146, v118
	v_mul_f32_e32 v147, v147, v119
	v_cvt_pk_bf16_f32 v139, v146, v147
	v_lshlrev_b32_e32 v144, 16, v140
	v_and_b32_e32 v145, 0xffff0000, v140
	v_mul_f32_e32 v144, v144, v120
	v_mul_f32_e32 v145, v145, v121
	v_cvt_pk_bf16_f32 v140, v144, v145
	v_lshlrev_b32_e32 v146, 16, v141
	v_and_b32_e32 v147, 0xffff0000, v141
	v_mul_f32_e32 v146, v146, v122
	v_mul_f32_e32 v147, v147, v123
	v_cvt_pk_bf16_f32 v141, v146, v147
	v_lshlrev_b32_e32 v144, 16, v142
	v_and_b32_e32 v145, 0xffff0000, v142
	v_mul_f32_e32 v144, v144, v124
	v_mul_f32_e32 v145, v145, v125
	v_cvt_pk_bf16_f32 v142, v144, v145
	v_lshlrev_b32_e32 v146, 16, v143
	v_and_b32_e32 v147, 0xffff0000, v143
	v_mul_f32_e32 v146, v146, v126
	v_mul_f32_e32 v147, v147, v127
	v_cvt_pk_bf16_f32 v143, v146, v147
	global_store_dwordx4 v[92:93], v[128:131], off
	global_store_dwordx4 v[92:93], v[132:135], off offset:16
	global_store_dwordx4 v[92:93], v[136:139], off offset:32
	global_store_dwordx4 v[92:93], v[140:143], off offset:48
	s_add_u32 s44, s44, 0x200
	s_addc_u32 s45, s45, 0
	s_add_u32 s46, s46, 0x100
	s_addc_u32 s47, s47, 0
	s_cmpk_lg_i32 s44, 0x1000
	s_barrier
	s_cbranch_scc1 .LBB0_154
	s_add_i32 s29, s29, s88
	v_readlane_b32 s0, v249, 56
	v_readlane_b32 s12, v249, 50
	v_readlane_b32 s1, v249, 57
	s_add_u32 s40, s40, s0
	v_readlane_b32 s13, v249, 51
	s_addc_u32 s41, s41, s1
	s_cmpk_gt_i32 s29, 0xff
	v_lshl_add_u64 v[40:41], v[40:41], 0, s[12:13]
	v_lshl_add_u64 v[42:43], v[42:43], 0, s[12:13]
	v_lshl_add_u64 v[44:45], v[44:45], 0, s[12:13]
	v_lshl_add_u64 v[46:47], v[46:47], 0, s[12:13]
	v_lshl_add_u64 v[48:49], v[48:49], 0, s[12:13]
	s_cbranch_scc0 .LBB0_149

; __device__ __forceinline__ unsigned cvt_pk_bf16(float lo, float hi) { f32x2 v = {lo, hi}; bf16x2_t b = __builtin_convertvector(v, bf16x2_t); return __builtin_bit_cast(unsigned, b); }
; __device__ __forceinline__ void prologue(const Ctx& C, const Args& a) {
;     ...
;     for (int m = C.gw; m < T; m += C.NGW) { const f32x4* row = (const f32x4*)(x + (size_t)m * D) + C.lane; u32x2* o8 = (u32x2*)(xb + (size_t)m * D) + C.lane;
; #pragma unroll
;         for (int j = 0; j < 4; ++j) { const f32x4 v = row[64 * j]; u32x2 w; w.x = cvt_pk_bf16(v.x, v.y); w.y = cvt_pk_bf16(v.z, v.w); o8[64 * j] = w; } }
.LBB0_524:
	global_load_dwordx4 v[4:7], v[2:3], off offset:-3072
	global_load_dwordx4 v[8:11], v[2:3], off offset:-2048
	global_load_dwordx4 v[12:15], v[2:3], off offset:-1024
	global_load_dwordx4 v[16:19], v[2:3], off
	s_add_i32 s18, s18, s60
	v_lshl_add_u64 v[2:3], v[2:3], 0, s[96:97]
	s_waitcnt vmcnt(3)
	v_cvt_pk_bf16_f32 v4, v4, v5
	v_cvt_pk_bf16_f32 v5, v6, v7
	global_store_dwordx2 v[0:1], v[4:5], off
	s_waitcnt vmcnt(3)
	v_cvt_pk_bf16_f32 v8, v8, v9
	v_cvt_pk_bf16_f32 v9, v10, v11
	global_store_dwordx2 v[0:1], v[8:9], off offset:512
	s_waitcnt vmcnt(3)
	v_cvt_pk_bf16_f32 v12, v12, v13
	v_cvt_pk_bf16_f32 v13, v14, v15
	global_store_dwordx2 v[0:1], v[12:13], off offset:1024
	s_waitcnt vmcnt(3)
	v_cvt_pk_bf16_f32 v16, v16, v17
	v_cvt_pk_bf16_f32 v17, v18, v19
	global_store_dwordx2 v[0:1], v[16:17], off offset:1536
	v_lshl_add_u64 v[0:1], v[0:1], 0, s[30:31]
	s_cmpk_gt_i32 s18, 0x7fff
	s_cbranch_scc0 .LBB0_524
